# P0->P1 grid barrier replaced by counters (sharded conversion-done + per-panel HN0), wave 0 polls then workgroup barrier; on top of v089
# baseline (speedup 1.0000x reference)
; #define tid tid_of(wave)
; #define lane lane_id()
; __global__ void __launch_bounds__(NWAVES * 64, 2) fwd_kernel(Args a) {
;     ...
;         for (int m = bx * (NWAVES * 64) + tid; m < NTOK; m += G * NWAVES * 64) { HSS1[m] = 0.f; HSS2[m] = 0.f; VSS[m] = 0.f; if (m < 2048) CNT[m] = 0u; }
;         for (int m = gw; m < NTOK; m += 2 * NGW) {
;             const int m2 = m + NGW; const bool two = m2 < NTOK;
;             const f32x4* xr = (const f32x4*)(x + (size_t)m * DM) + lane; const f32x4* xr2 = (const f32x4*)(x + (size_t)(two ? m2 : m) * DM) + lane;
;             f32x4 v[8], v2[8]; float ss = 0.f, ss2 = 0.f;
; #pragma unroll
;             for (int j = 0; j < 8; ++j) { v[j] = __builtin_nontemporal_load(xr + 64 * j); v2[j] = __builtin_nontemporal_load(xr2 + 64 * j); }
; #pragma unroll
;             for (int j = 0; j < 8; ++j) { ss += (v[j][0] * v[j][0] + v[j][1] * v[j][1]) + (v[j][2] * v[j][2] + v[j][3] * v[j][3]); ss2 += (v2[j][0] * v2[j][0] + v2[j][1] * v2[j][1]) + (v2[j][2] * v2[j][2] + v2[j][3] * v2[j][3]); }
;             const float ms = wave_sum(ss) * (1.0f / DM) + EPS, ms2 = wave_sum(ss2) * (1.0f / DM) + EPS;
.LBB0_39:
	v_add_co_u32_e32 v4, vcc, 0x200000, v2
	s_nop 1
	v_addc_co_u32_e32 v5, vcc, 0, v3, vcc
	global_store_dword v[4:5], v1, off sc1
	v_add_co_u32_e32 v4, vcc, 0x300000, v2
	s_nop 1
	v_addc_co_u32_e32 v5, vcc, 0, v3, vcc
	v_cmp_gt_i32_e32 vcc, s5, v0
	global_store_dword v[4:5], v1, off sc1
	global_store_dword v[2:3], v1, off sc1
	s_and_saveexec_b64 s[12:13], vcc
	s_cbranch_execz .LBB0_38
	v_add_co_u32_e32 v4, vcc, 0x310000, v2
	s_nop 1
	v_addc_co_u32_e32 v5, vcc, 0, v3, vcc
	global_store_dword v[4:5], v1, off sc1
	s_branch .LBB0_38
.LBB0_41:
	s_or_b64 exec, exec, s[0:1]
	s_cmpk_gt_i32 s96, 0x1fff
	s_cbranch_scc1 .LBB0_63
	v_and_b32_e32 v0, 64, v195
	v_add_u32_e32 v0, 64, v0
	v_xor_b32_e32 v1, 1, v195
	v_cmp_lt_i32_e32 vcc, v1, v0
	v_readlane_b32 s8, v248, 6
	v_lshlrev_b32_e32 v64, 4, v195
	v_cndmask_b32_e32 v1, v195, v1, vcc
	v_lshlrev_b32_e32 v74, 2, v1
	v_xor_b32_e32 v1, 2, v195
	v_cmp_lt_i32_e32 vcc, v1, v0
	v_mov_b32_e32 v65, 0
	v_readlane_b32 s9, v248, 7
	v_cndmask_b32_e32 v1, v195, v1, vcc
	v_lshlrev_b32_e32 v75, 2, v1
	v_xor_b32_e32 v1, 4, v195
	v_cmp_lt_i32_e32 vcc, v1, v0
	v_readlane_b32 s4, v248, 27
	v_readlane_b32 s12, v248, 10
	v_cndmask_b32_e32 v1, v195, v1, vcc
	v_lshlrev_b32_e32 v76, 2, v1
	v_xor_b32_e32 v1, 8, v195
	v_cmp_lt_i32_e32 vcc, v1, v0
	v_readlane_b32 s18, v248, 16
	v_lshl_add_u64 v[66:67], s[8:9], 0, v[64:65]
	v_cndmask_b32_e32 v1, v195, v1, vcc
	v_lshlrev_b32_e32 v77, 2, v1
	v_xor_b32_e32 v1, 16, v195
	v_cmp_lt_i32_e32 vcc, v1, v0
	v_lshlrev_b32_e32 v64, 3, v195
	v_readlane_b32 s5, v248, 28
	v_cndmask_b32_e32 v1, v195, v1, vcc
	v_lshlrev_b32_e32 v78, 2, v1
	v_xor_b32_e32 v1, 32, v195
	v_cmp_lt_i32_e32 vcc, v1, v0
	s_ashr_i32 s71, s70, 31
	v_cmp_eq_u32_e64 s[0:1], 0, v195
	v_cndmask_b32_e32 v0, v195, v1, vcc
	v_lshlrev_b32_e32 v79, 2, v0
	v_lshl_add_u64 v[68:69], s[4:5], 0, v[64:65]
	s_movk_i32 s18, 0x1000
	v_mov_b32_e32 v64, 0x358637bd
	s_lshl_b64 s[8:9], s[70:71], 2
	s_mov_b32 s12, s96
	v_readlane_b32 s10, v248, 8
	v_readlane_b32 s11, v248, 9
	v_readlane_b32 s13, v248, 11
	v_readlane_b32 s14, v248, 12
	v_readlane_b32 s15, v248, 13
	v_readlane_b32 s16, v248, 14
	v_readlane_b32 s17, v248, 15
	v_readlane_b32 s19, v248, 17
	v_readlane_b32 s20, v248, 18
	v_readlane_b32 s21, v248, 19
	v_readlane_b32 s22, v248, 20
	v_readlane_b32 s23, v248, 21
	s_mov_b32 s32, 0
	s_branch .LBB0_44

; #define lane lane_id()
; __global__ void __launch_bounds__(NWAVES * 64, 2) fwd_kernel(Args a) {
;     ...
;         for (int m = gw; m < NTOK; m += 2 * NGW) {
;             const int m2 = m + NGW; const bool two = m2 < NTOK;
;             const f32x4* xr = (const f32x4*)(x + (size_t)m * DM) + lane; const f32x4* xr2 = (const f32x4*)(x + (size_t)(two ? m2 : m) * DM) + lane;
;             f32x4 v[8], v2[8]; float ss = 0.f, ss2 = 0.f;
; #pragma unroll
;             for (int j = 0; j < 8; ++j) { v[j] = __builtin_nontemporal_load(xr + 64 * j); v2[j] = __builtin_nontemporal_load(xr2 + 64 * j); }
; #pragma unroll
;             for (int j = 0; j < 8; ++j) { ss += (v[j][0] * v[j][0] + v[j][1] * v[j][1]) + (v[j][2] * v[j][2] + v[j][3] * v[j][3]); ss2 += (v2[j][0] * v2[j][0] + v2[j][1] * v2[j][1]) + (v2[j][2] * v2[j][2] + v2[j][3] * v2[j][3]); }
;             const float ms = wave_sum(ss) * (1.0f / DM) + EPS, ms2 = wave_sum(ss2) * (1.0f / DM) + EPS;
;             const float rstd = __builtin_amdgcn_rsqf(ms), rstd2 = __builtin_amdgcn_rsqf(ms2);
;             if (lane == 0) { IRS0[m] = __builtin_amdgcn_sqrtf(ms); if (two) IRS0[m2] = __builtin_amdgcn_sqrtf(ms2); }
.LBB0_44:
	s_ashr_i32 s13, s12, 31
	s_lshl_b64 s[4:5], s[12:13], 13
	s_add_i32 s10, s12, s70
	s_cmpk_lt_i32 s10, 0x2000
	v_lshl_add_u64 v[0:1], v[66:67], 0, s[4:5]
	s_cselect_b64 s[4:5], -1, 0
	global_load_dwordx4 v[20:23], v[0:1], off nt
	global_load_dwordx4 v[16:19], v[0:1], off offset:1024 nt
	global_load_dwordx4 v[12:15], v[0:1], off offset:2048 nt
	global_load_dwordx4 v[8:11], v[0:1], off offset:3072 nt
	v_cndmask_b32_e64 v72, 0, 1, s[4:5]
	s_and_b64 s[4:5], s[4:5], exec
	s_cselect_b32 s4, s10, s12
	v_add_co_u32_e32 v24, vcc, s18, v0
	s_ashr_i32 s5, s4, 31
	s_nop 0
	v_addc_co_u32_e32 v25, vcc, 0, v1, vcc
	s_lshl_b64 s[4:5], s[4:5], 13
	global_load_dwordx4 v[4:7], v[24:25], off nt
	global_load_dwordx4 v[0:3], v[24:25], off offset:1024 nt
	v_lshl_add_u64 v[26:27], v[66:67], 0, s[4:5]
	global_load_dwordx4 v[60:63], v[26:27], off nt
	global_load_dwordx4 v[56:59], v[26:27], off offset:1024 nt
	global_load_dwordx4 v[52:55], v[26:27], off offset:2048 nt
	global_load_dwordx4 v[48:51], v[26:27], off offset:3072 nt
	v_add_co_u32_e32 v26, vcc, s18, v26
	v_cmp_ne_u32_e64 s[4:5], 1, v72
	s_nop 0
	v_addc_co_u32_e32 v27, vcc, 0, v27, vcc
	global_load_dwordx4 v[44:47], v[26:27], off nt
	global_load_dwordx4 v[40:43], v[26:27], off offset:1024 nt
	global_load_dwordx4 v[36:39], v[24:25], off offset:2048 nt
	global_load_dwordx4 v[32:35], v[26:27], off offset:2048 nt
	global_load_dwordx4 v[28:31], v[24:25], off offset:3072 nt
	s_nop 0
	global_load_dwordx4 v[24:27], v[26:27], off offset:3072 nt
	s_waitcnt vmcnt(15)
	s_cmp_lg_u32 s32, 0
	s_cbranch_scc1 .Lp0_conv_posted
	s_mov_b32 s32, 1
	s_and_b32 s98, s96, 7
	s_lshl_b32 s98, s98, 6
	s_add_i32 s98, s98, 0x3600
	v_mov_b32_e32 v236, s98
	v_mov_b32_e32 v237, 1
	s_mov_b64 s[100:101], exec
	s_mov_b64 exec, 1
	global_atomic_add v236, v237, s[68:69]
	s_mov_b64 exec, s[100:101]
.Lp0_conv_posted:
	v_mul_f32_e32 v70, v21, v21
	v_mul_f32_e32 v71, v23, v23
	s_waitcnt vmcnt(14)
	v_mul_f32_e32 v73, v17, v17
	v_mul_f32_e32 v80, v19, v19
	s_waitcnt vmcnt(13)
	v_mul_f32_e32 v81, v13, v13
	v_mul_f32_e32 v82, v15, v15
	v_fmac_f32_e32 v70, v20, v20
	v_fmac_f32_e32 v71, v22, v22
	v_fmac_f32_e32 v73, v16, v16
	v_fmac_f32_e32 v80, v18, v18
	s_waitcnt vmcnt(12)
	v_mul_f32_e32 v83, v9, v9
	v_mul_f32_e32 v84, v11, v11
	v_fmac_f32_e32 v81, v12, v12
	v_fmac_f32_e32 v82, v14, v14
	v_add_f32_e32 v70, v70, v71
	v_add_f32_e32 v71, v73, v80
	v_fmac_f32_e32 v83, v8, v8
	v_fmac_f32_e32 v84, v10, v10
	v_add_f32_e32 v73, v81, v82
	v_add_f32_e32 v70, v70, v71
	v_add_f32_e32 v80, v83, v84
	v_add_f32_e32 v70, v70, v73
	s_waitcnt vmcnt(11)
	v_mul_f32_e32 v85, v5, v5
	v_mul_f32_e32 v86, v7, v7
	v_add_f32_e32 v70, v70, v80
	s_waitcnt vmcnt(9)
	v_mul_f32_e32 v73, v61, v61
	v_mul_f32_e32 v80, v63, v63
	s_waitcnt vmcnt(8)
	v_mul_f32_e32 v81, v57, v57
	v_mul_f32_e32 v82, v59, v59
	v_fmac_f32_e32 v85, v4, v4
	v_fmac_f32_e32 v86, v6, v6
	s_waitcnt vmcnt(7)
	v_mul_f32_e32 v83, v53, v53
	v_mul_f32_e32 v84, v55, v55
	v_fmac_f32_e32 v73, v60, v60
	v_fmac_f32_e32 v80, v62, v62
	v_fmac_f32_e32 v81, v56, v56
	v_fmac_f32_e32 v82, v58, v58
	v_add_f32_e32 v71, v85, v86
	s_waitcnt vmcnt(6)
	v_mul_f32_e32 v85, v49, v49
	v_mul_f32_e32 v86, v51, v51
	v_fmac_f32_e32 v83, v52, v52
	v_fmac_f32_e32 v84, v54, v54
	v_add_f32_e32 v73, v73, v80
	v_add_f32_e32 v80, v81, v82
	v_add_f32_e32 v70, v70, v71
	v_fmac_f32_e32 v85, v48, v48
	v_fmac_f32_e32 v86, v50, v50
	s_waitcnt vmcnt(5)
	v_mul_f32_e32 v71, v45, v45
	v_mul_f32_e32 v88, v47, v47
	v_add_f32_e32 v81, v83, v84
	v_add_f32_e32 v73, v73, v80
	v_add_f32_e32 v82, v85, v86
	v_fmac_f32_e32 v71, v44, v44
	v_fmac_f32_e32 v88, v46, v46
	v_add_f32_e32 v73, v73, v81
	v_add_f32_e32 v71, v71, v88
	v_add_f32_e32 v73, v73, v82
	v_mul_f32_e32 v87, v1, v1
	v_add_f32_e32 v71, v73, v71
	v_mul_f32_e32 v73, v3, v3
	v_fmac_f32_e32 v87, v0, v0
	v_fmac_f32_e32 v73, v2, v2
	v_add_f32_e32 v73, v87, v73
	v_add_f32_e32 v70, v70, v73
	s_waitcnt vmcnt(4)
	v_mul_f32_e32 v73, v41, v41
	v_mul_f32_e32 v80, v43, v43
	v_fmac_f32_e32 v73, v40, v40
	v_fmac_f32_e32 v80, v42, v42
	v_add_f32_e32 v73, v73, v80
	v_add_f32_e32 v71, v71, v73
	s_waitcnt vmcnt(3)
	v_mul_f32_e32 v73, v37, v37
	v_mul_f32_e32 v80, v39, v39
	v_fmac_f32_e32 v73, v36, v36
	v_fmac_f32_e32 v80, v38, v38
	v_add_f32_e32 v73, v73, v80
	v_add_f32_e32 v70, v70, v73
	s_waitcnt vmcnt(2)
	v_mul_f32_e32 v73, v33, v33
	v_mul_f32_e32 v80, v35, v35
	v_fmac_f32_e32 v73, v32, v32
	v_fmac_f32_e32 v80, v34, v34
	v_add_f32_e32 v73, v73, v80
	v_add_f32_e32 v71, v71, v73
	s_waitcnt vmcnt(1)
	v_mul_f32_e32 v73, v29, v29
	v_mul_f32_e32 v80, v31, v31
	v_fmac_f32_e32 v73, v28, v28
	v_fmac_f32_e32 v80, v30, v30
	v_add_f32_e32 v73, v73, v80
	v_add_f32_e32 v70, v70, v73
	s_waitcnt vmcnt(0)
	v_mul_f32_e32 v73, v25, v25
	v_mul_f32_e32 v80, v27, v27
	v_fmac_f32_e32 v73, v24, v24
	v_fmac_f32_e32 v80, v26, v26
	v_add_f32_e32 v73, v73, v80
	v_add_f32_e32 v71, v71, v73
	ds_bpermute_b32 v80, v74, v70
	ds_bpermute_b32 v73, v74, v71
	s_waitcnt lgkmcnt(1)
	v_add_f32_e32 v70, v70, v80
	s_waitcnt lgkmcnt(0)
	v_add_f32_e32 v71, v71, v73
	ds_bpermute_b32 v80, v75, v70
	ds_bpermute_b32 v73, v75, v71
	s_waitcnt lgkmcnt(1)
	v_add_f32_e32 v70, v70, v80
	s_waitcnt lgkmcnt(0)
	v_add_f32_e32 v71, v71, v73
	ds_bpermute_b32 v80, v76, v70
	ds_bpermute_b32 v73, v76, v71
	s_waitcnt lgkmcnt(1)
	v_add_f32_e32 v70, v70, v80
	s_waitcnt lgkmcnt(0)
	v_add_f32_e32 v71, v71, v73
	ds_bpermute_b32 v80, v77, v70
	ds_bpermute_b32 v73, v77, v71
	s_waitcnt lgkmcnt(1)
	v_add_f32_e32 v70, v70, v80
	s_waitcnt lgkmcnt(0)
	v_add_f32_e32 v71, v71, v73
	ds_bpermute_b32 v80, v78, v70
	ds_bpermute_b32 v73, v78, v71
	s_waitcnt lgkmcnt(1)
	v_add_f32_e32 v70, v70, v80
	s_waitcnt lgkmcnt(0)
	v_add_f32_e32 v71, v71, v73
	ds_bpermute_b32 v80, v79, v70
	ds_bpermute_b32 v73, v79, v71
	s_waitcnt lgkmcnt(1)
	v_add_f32_e32 v70, v70, v80
	s_waitcnt lgkmcnt(0)
	v_add_f32_e32 v71, v71, v73
	v_fmamk_f32 v70, v70, 0x3a000000, v64
	v_fmamk_f32 v71, v71, 0x3a000000, v64
	s_and_saveexec_b64 s[14:15], s[0:1]
	s_cbranch_execz .LBB0_47
	v_sqrt_f32_e32 v72, v70
	s_lshl_b64 s[16:17], s[12:13], 2
	v_readlane_b32 s20, v248, 23
	v_readlane_b32 s21, v248, 24
	s_add_u32 s16, s20, s16
	s_addc_u32 s17, s21, s17
	s_and_b64 vcc, exec, s[4:5]
	global_store_dword v65, v72, s[16:17]
	s_cbranch_vccnz .LBB0_47
	v_sqrt_f32_e32 v72, v71
	s_add_u32 s16, s16, s8
	s_addc_u32 s17, s17, s9
	global_store_dword v65, v72, s[16:17]

; __device__ __forceinline__ int tid_of(int wave) { return wave * 64 + lane_id(); }
; __device__ __forceinline__ unsigned xb_ld(unsigned* p)              { return __hip_atomic_load(p, __ATOMIC_RELAXED, __HIP_MEMORY_SCOPE_AGENT); }
; __device__ __forceinline__ unsigned xb_add(unsigned* p, unsigned v) { return __hip_atomic_fetch_add(p, v, __ATOMIC_RELAXED, __HIP_MEMORY_SCOPE_AGENT); }
; #define XB_SPIN(cond, bar) do { unsigned _sp = 0; while (cond) { __builtin_amdgcn_s_sleep(1); \
;     if ((++_sp & 255u) == 0u) { if (xb_ld(&(bar)[XB_TMO])) break; if (_sp > XB_SPIN_CAP) { atomicAdd(&(bar)[XB_TMO], 1u); break; } } } } while (0)
; __device__ __forceinline__ void xcd_barrier(const XcdBarrier& b) {
;     asm volatile("s_waitcnt vmcnt(0)" ::: "memory");
;     __syncthreads();
;     if (tid_of(b.w) == 0) {
;         unsigned* bar = b.bar;
;         __builtin_amdgcn_s_waitcnt(0);
;         unsigned nloc = b.st[0], nx = b.st[1];
;         if (nloc == 0u) { xcd_barrier_complete(bar, b.x, nloc, nx); b.st[0] = nloc; b.st[1] = nx; }
;         const unsigned old = xb_add(&bar[XB_XSUB(b.x)], 1u);
;         const unsigned gen = old / nloc;
;         if (old + 1u == (gen + 1u) * nloc) {
;             __builtin_amdgcn_fence(__ATOMIC_RELEASE, "agent");
;             asm volatile("s_waitcnt vmcnt(0)" ::: "memory");
;             const unsigned og = xb_add(&bar[XB_TOP], 1u);
;             const unsigned tg = og / nx;
;             if (og + 1u == (tg + 1u) * nx) xb_add(&bar[XB_TOPGEN], 1u);
;             else XB_SPIN(xb_ld(&bar[XB_TOPGEN]) == tg, bar);
;             __builtin_amdgcn_fence(__ATOMIC_ACQUIRE, "agent");
;             xb_add(&bar[XB_XGEN(b.x)], 1u);
;             asm volatile("s_waitcnt vmcnt(0)" ::: "memory");
;         } else {
;             XB_SPIN(xb_ld(&bar[XB_XGEN(b.x)]) == gen, bar);
;             __builtin_amdgcn_fence(__ATOMIC_ACQUIRE, "agent");
;             asm volatile("s_waitcnt vmcnt(0)" ::: "memory");
;         }
;     }
;     __syncthreads();
; }
.LBB0_63:
	s_waitcnt vmcnt(0)
	s_lshr_b32 s98, s96, 8
	s_lshl_b32 s98, s98, 6
	s_add_i32 s98, s98, 0x3800
	v_mov_b32_e32 v236, s98
	v_mov_b32_e32 v237, 1
	s_mov_b64 s[100:101], exec
	s_mov_b64 exec, 1
	global_atomic_add v236, v237, s[68:69]
	s_mov_b64 exec, s[100:101]
	s_add_i32 s98, s98, 0x200
	v_mov_b32_e32 v236, s98
	v_mov_b32_e32 v237, 1
	s_mov_b64 s[100:101], exec
	s_mov_b64 exec, 1
	global_atomic_add v236, v237, s[68:69]
	s_mov_b64 exec, s[100:101]
	s_add_i32 s98, s98, 0x200
	v_mov_b32_e32 v236, s98
	v_mov_b32_e32 v237, 1
	s_mov_b64 s[100:101], exec
	s_mov_b64 exec, 1
	global_atomic_add v236, v237, s[68:69]
	s_mov_b64 exec, s[100:101]
	s_add_i32 s98, s98, 0x200
	v_mov_b32_e32 v236, s98
	v_mov_b32_e32 v237, 1
	s_mov_b64 s[100:101], exec
	s_mov_b64 exec, 1
	global_atomic_add v236, v237, s[68:69]
	s_mov_b64 exec, s[100:101]
	v_readlane_b32 s8, v248, 0
	v_readlane_b32 s9, v248, 1
	s_cmp_gt_i32 s9, 1
	s_cselect_b64 s[0:1], -1, 0
	s_and_b64 s[4:5], s[6:7], s[0:1]
	s_andn2_b64 vcc, exec, s[4:5]
	v_readlane_b32 s10, v248, 2
	v_readlane_b32 s11, v248, 3
	s_cmpk_eq_i32 s88, 0x100
	s_cbranch_scc1 .LBB0_117
	s_cbranch_vccnz .LBB0_117
	s_waitcnt vmcnt(0)
	s_barrier
	s_mov_b64 s[4:5], exec
	v_readlane_b32 s6, v248, 4
	v_readlane_b32 s7, v248, 5
	s_and_b64 s[6:7], s[4:5], s[6:7]
	s_mov_b64 exec, s[6:7]
	s_cbranch_execz .LBB0_116
	s_add_i32 s6, 0, 0x24fe0
	v_mov_b32_e32 v0, s6
	s_waitcnt vmcnt(0) expcnt(0) lgkmcnt(0)
	ds_read_b32 v2, v0
	s_add_i32 s6, 0, 0x24fe4
	v_mov_b32_e32 v0, s6
	ds_read_b32 v0, v0
	s_waitcnt lgkmcnt(1)
	v_cmp_ne_u32_e32 vcc, 0, v2
	s_cbranch_vccnz .LBB0_80
	s_add_u32 s6, s68, 0x1000
	s_addc_u32 s7, s69, 0
	s_add_u32 s8, s68, 0x1100
	s_addc_u32 s9, s69, 0
	s_add_u32 s10, s68, 0x1200
	s_addc_u32 s11, s69, 0
	s_mul_i32 s20, s89, s90
	s_add_u32 s12, s68, 0x1300
	s_mul_i32 s20, s20, s88
	s_addc_u32 s13, s69, 0
	s_mov_b32 s21, 1
	v_mov_b32_e32 v16, 0
	s_branch .LBB0_68

; #define lane lane_id()
; __global__ void __launch_bounds__(NWAVES * 64, 2) fwd_kernel(Args a) {
;     ...
;     if (IN(1)) for (int rep = 0; rep < NREP(1); ++rep) {
;         pg8::Gemm g{HN0, WT1, NTOK, 3 * GW, DM}; pg8::ConvOrder S; S.init(NTOK, 3 * GW, G, bx);
;         S.w2 = a_w_out; S.w3 = b_w_in; S.w4 = b_w_out; S.g1 = norm_g + DM; S.t2 = WT2; S.t3 = WT3; S.t4 = WT4; S.gw = gw; S.ngw = NGW; S.trigger = (G == 256) ? CONV_TRIGGER : 0; S.ln = lane; S.sw = lds + 131072 + wave * 2048; S.n_done = 0;
;         pg8::EpiGmlpIn E{U, V, VSS};
;         pg8::gemm_phase<pg8::EpiGmlpIn, pg8::ConvOrder, GEMM_ALIGN, GEMM_SP2>(lds, g, S, E, wave);
.LBB0_120:
	s_andn2_b64 vcc, exec, s[0:1]
	s_cbranch_vccnz .LBB0_207
	s_cmpk_lg_i32 s88, 0x100
	s_cbranch_scc1 .Lp1_nowait
	v_readlane_b32 s100, v248, 0
	s_cmp_gt_i32 s100, 0
	s_cbranch_scc1 .Lp1_nowait
	s_cmp_gt_u32 s67, 63
	s_cbranch_scc1 .Lp1_meet
	v_mov_b32_e32 v236, 0x3600
	s_mov_b32 s100, 0
.Lp1_poll_c0:
	global_load_dword v237, v236, s[68:69] sc1
	s_waitcnt vmcnt(0)
	v_readfirstlane_b32 s101, v237
	s_cmpk_ge_u32 s101, 0x100
	s_cbranch_scc1 .Lp1_got_c0
	s_add_i32 s100, s100, 1
	s_cmp_lt_u32 s100, 0x10000
	s_cbranch_scc0 .Lp1_got_c0
	s_sleep 2
	s_branch .Lp1_poll_c0
.Lp1_got_c0:
	v_mov_b32_e32 v236, 0x3640
	s_mov_b32 s100, 0

; #define lane lane_id()
; __global__ void __launch_bounds__(NWAVES * 64, 2) fwd_kernel(Args a) {
;     ...
;     if (IN(1)) for (int rep = 0; rep < NREP(1); ++rep) {
;         pg8::Gemm g{HN0, WT1, NTOK, 3 * GW, DM}; pg8::ConvOrder S; S.init(NTOK, 3 * GW, G, bx);
;         S.w2 = a_w_out; S.w3 = b_w_in; S.w4 = b_w_out; S.g1 = norm_g + DM; S.t2 = WT2; S.t3 = WT3; S.t4 = WT4; S.gw = gw; S.ngw = NGW; S.trigger = (G == 256) ? CONV_TRIGGER : 0; S.ln = lane; S.sw = lds + 131072 + wave * 2048; S.n_done = 0;
;         pg8::EpiGmlpIn E{U, V, VSS};
;         pg8::gemm_phase<pg8::EpiGmlpIn, pg8::ConvOrder, GEMM_ALIGN, GEMM_SP2>(lds, g, S, E, wave);
.Lp1_got_c1:
	v_mov_b32_e32 v236, 0x3680
	s_mov_b32 s100, 0

; #define lane lane_id()
; __global__ void __launch_bounds__(NWAVES * 64, 2) fwd_kernel(Args a) {
;     ...
;     if (IN(1)) for (int rep = 0; rep < NREP(1); ++rep) {
;         pg8::Gemm g{HN0, WT1, NTOK, 3 * GW, DM}; pg8::ConvOrder S; S.init(NTOK, 3 * GW, G, bx);
;         S.w2 = a_w_out; S.w3 = b_w_in; S.w4 = b_w_out; S.g1 = norm_g + DM; S.t2 = WT2; S.t3 = WT3; S.t4 = WT4; S.gw = gw; S.ngw = NGW; S.trigger = (G == 256) ? CONV_TRIGGER : 0; S.ln = lane; S.sw = lds + 131072 + wave * 2048; S.n_done = 0;
;         pg8::EpiGmlpIn E{U, V, VSS};
;         pg8::gemm_phase<pg8::EpiGmlpIn, pg8::ConvOrder, GEMM_ALIGN, GEMM_SP2>(lds, g, S, E, wave);
.Lp1_got_c2:
	v_mov_b32_e32 v236, 0x36c0
	s_mov_b32 s100, 0

; #define lane lane_id()
; __global__ void __launch_bounds__(NWAVES * 64, 2) fwd_kernel(Args a) {
;     ...
;     if (IN(1)) for (int rep = 0; rep < NREP(1); ++rep) {
;         pg8::Gemm g{HN0, WT1, NTOK, 3 * GW, DM}; pg8::ConvOrder S; S.init(NTOK, 3 * GW, G, bx);
;         S.w2 = a_w_out; S.w3 = b_w_in; S.w4 = b_w_out; S.g1 = norm_g + DM; S.t2 = WT2; S.t3 = WT3; S.t4 = WT4; S.gw = gw; S.ngw = NGW; S.trigger = (G == 256) ? CONV_TRIGGER : 0; S.ln = lane; S.sw = lds + 131072 + wave * 2048; S.n_done = 0;
;         pg8::EpiGmlpIn E{U, V, VSS};
;         pg8::gemm_phase<pg8::EpiGmlpIn, pg8::ConvOrder, GEMM_ALIGN, GEMM_SP2>(lds, g, S, E, wave);
.Lp1_got_c3:
	v_mov_b32_e32 v236, 0x3700
	s_mov_b32 s100, 0

; #define lane lane_id()
; __global__ void __launch_bounds__(NWAVES * 64, 2) fwd_kernel(Args a) {
;     ...
;     if (IN(1)) for (int rep = 0; rep < NREP(1); ++rep) {
;         pg8::Gemm g{HN0, WT1, NTOK, 3 * GW, DM}; pg8::ConvOrder S; S.init(NTOK, 3 * GW, G, bx);
;         S.w2 = a_w_out; S.w3 = b_w_in; S.w4 = b_w_out; S.g1 = norm_g + DM; S.t2 = WT2; S.t3 = WT3; S.t4 = WT4; S.gw = gw; S.ngw = NGW; S.trigger = (G == 256) ? CONV_TRIGGER : 0; S.ln = lane; S.sw = lds + 131072 + wave * 2048; S.n_done = 0;
;         pg8::EpiGmlpIn E{U, V, VSS};
;         pg8::gemm_phase<pg8::EpiGmlpIn, pg8::ConvOrder, GEMM_ALIGN, GEMM_SP2>(lds, g, S, E, wave);
.Lp1_got_c4:
	v_mov_b32_e32 v236, 0x3740
	s_mov_b32 s100, 0

; #define lane lane_id()
; __global__ void __launch_bounds__(NWAVES * 64, 2) fwd_kernel(Args a) {
;     ...
;     if (IN(1)) for (int rep = 0; rep < NREP(1); ++rep) {
;         pg8::Gemm g{HN0, WT1, NTOK, 3 * GW, DM}; pg8::ConvOrder S; S.init(NTOK, 3 * GW, G, bx);
;         S.w2 = a_w_out; S.w3 = b_w_in; S.w4 = b_w_out; S.g1 = norm_g + DM; S.t2 = WT2; S.t3 = WT3; S.t4 = WT4; S.gw = gw; S.ngw = NGW; S.trigger = (G == 256) ? CONV_TRIGGER : 0; S.ln = lane; S.sw = lds + 131072 + wave * 2048; S.n_done = 0;
;         pg8::EpiGmlpIn E{U, V, VSS};
;         pg8::gemm_phase<pg8::EpiGmlpIn, pg8::ConvOrder, GEMM_ALIGN, GEMM_SP2>(lds, g, S, E, wave);
.Lp1_got_c5:
	v_mov_b32_e32 v236, 0x3780
	s_mov_b32 s100, 0

; #define lane lane_id()
; __global__ void __launch_bounds__(NWAVES * 64, 2) fwd_kernel(Args a) {
;     ...
;     if (IN(1)) for (int rep = 0; rep < NREP(1); ++rep) {
;         pg8::Gemm g{HN0, WT1, NTOK, 3 * GW, DM}; pg8::ConvOrder S; S.init(NTOK, 3 * GW, G, bx);
;         S.w2 = a_w_out; S.w3 = b_w_in; S.w4 = b_w_out; S.g1 = norm_g + DM; S.t2 = WT2; S.t3 = WT3; S.t4 = WT4; S.gw = gw; S.ngw = NGW; S.trigger = (G == 256) ? CONV_TRIGGER : 0; S.ln = lane; S.sw = lds + 131072 + wave * 2048; S.n_done = 0;
;         pg8::EpiGmlpIn E{U, V, VSS};
;         pg8::gemm_phase<pg8::EpiGmlpIn, pg8::ConvOrder, GEMM_ALIGN, GEMM_SP2>(lds, g, S, E, wave);
.Lp1_got_c6:
	v_mov_b32_e32 v236, 0x37c0
	s_mov_b32 s100, 0

; #define lane lane_id()
; __global__ void __launch_bounds__(NWAVES * 64, 2) fwd_kernel(Args a) {
;     ...
;     if (IN(1)) for (int rep = 0; rep < NREP(1); ++rep) {
;         pg8::Gemm g{HN0, WT1, NTOK, 3 * GW, DM}; pg8::ConvOrder S; S.init(NTOK, 3 * GW, G, bx);
;         S.w2 = a_w_out; S.w3 = b_w_in; S.w4 = b_w_out; S.g1 = norm_g + DM; S.t2 = WT2; S.t3 = WT3; S.t4 = WT4; S.gw = gw; S.ngw = NGW; S.trigger = (G == 256) ? CONV_TRIGGER : 0; S.ln = lane; S.sw = lds + 131072 + wave * 2048; S.n_done = 0;
;         pg8::EpiGmlpIn E{U, V, VSS};
;         pg8::gemm_phase<pg8::EpiGmlpIn, pg8::ConvOrder, GEMM_ALIGN, GEMM_SP2>(lds, g, S, E, wave);
.Lp1_got_c7:
	s_lshl_b32 s98, s44, 6
	s_add_i32 s98, s98, 0x3800
	v_mov_b32_e32 v236, s98
	s_mov_b32 s100, 0

; #define PG8_STAGE(bufoff, gbase, voff) do { _Pragma("unroll") for (int _i = 0; _i < 2; ++_i) \
;         __builtin_amdgcn_global_load_lds((const unsigned*)((const char*)(gbase) + (voff)[_i]), (PG8_LAS unsigned*)(lds + (bufoff) + ldsw + _i * 8192), 16, 0, 0); } while (0)
; #define PG8_BAR __builtin_amdgcn_s_barrier()
; #define tid tid_of(wave)
; template <class Epi, class Sched, bool ALIGN_EPI = false, bool SP2 = false>
; __device__ __forceinline__ void gemm_phase(PG8_LAS unsigned char* lds, const Gemm g, const Sched& S, const Epi& E, const int wave_) {
;     ...
;     for (int i = 0; i < 2; ++i) { int R, C; stage_rc(tid * 16 + i * 8192, R, C); const int Rb = Epi::PERM ? ((R & ~31) + perm32(R & 31)) : R;
;         voffA[i] = (unsigned)(R * K + C) * 2u; voffB[i] = (unsigned)(Rb * K + C) * 2u; }
;     const size_t kstep = (size_t)(BK * 2);
;     const size_t hstep = (size_t)HALF * K * 2;
;     const size_t tstep = 2 * hstep;
;     const unsigned ldsw = (unsigned)wid * 1024u;
;     const int aoff = lds_byte(wr * 64 + fr, fq * 8), boff = lds_byte(wc * 32 + fr, fq * 8);
;     ...
;     Unit cur, nxt; int ui = 0;
;     if (!S.next(0, cur)) return;
;     f32x4 acc[2][2][4][2];
; #pragma unroll
;     for (int a = 0; a < 2; ++a)
; #pragma unroll
;         for (int b = 0; b < 2; ++b)
; #pragma unroll
;             for (int m = 0; m < 4; ++m)
; #pragma unroll
;                 for (int n = 0; n < 2; ++n) acc[a][b][m][n] = (f32x4){0.f, 0.f, 0.f, 0.f};
;     bf16x8 At[4][2], B0[2][2], B1[2][2];
;     const char* cA = (const char*)g.A + (size_t)cur.pm * tstep; const char* cB = (const char*)g.Bt + (size_t)cur.pn * tstep;
;     S.a_ready(cur);
;     if constexpr (SP2) {
;         PG8_STAGE(PG8_SB(0, 0), cB, voffB); PG8_STAGE(PG8_SB(0, 1), cB + hstep, voffB); PG8_STAGE(PG8_SA(0, 0), cA, voffA); PG8_STAGE(PG8_SA(0, 1), cA + hstep, voffA);
;         if (wr == 1) PG8_BAR;
.Lp1_got_p:
.Lp1_meet:
	s_barrier
.Lp1_nowait:
	v_writelane_b32 v248, s76, 37
	s_lshr_b32 s0, s67, 8
	v_mov_b32_e32 v131, 0
	v_writelane_b32 v248, s77, 38
	v_writelane_b32 v248, s78, 39
	v_writelane_b32 v248, s79, 40
	v_writelane_b32 v248, s80, 41
	v_writelane_b32 v248, s81, 42
	v_writelane_b32 v248, s82, 43
	v_writelane_b32 v248, s83, 44
	v_mov_b32_e32 v135, v131
	v_readlane_b32 s1, v248, 22
	s_lshl_b32 s52, s1, 10
	v_lshl_add_u32 v0, v195, 4, s52
	v_ashrrev_i32_e32 v1, 31, v0
	v_lshrrev_b32_e32 v1, 22, v1
	v_add_u32_e32 v1, v0, v1
	v_ashrrev_i32_e32 v8, 10, v1
	v_mul_i32_i24_e32 v1, 0x400, v8
	v_sub_u32_e32 v1, v0, v1
	v_lshrrev_b32_e32 v2, 4, v1
	v_bitop3_b32 v1, v2, v1, 32 bitop3:0x6c
	v_ashrrev_i32_e32 v3, 31, v1
	v_lshrrev_b32_e32 v3, 26, v3
	v_add_u32_e32 v3, v1, v3
	v_lshlrev_b32_e32 v2, 3, v8
	v_ashrrev_i32_e32 v9, 6, v3
	v_and_b32_e32 v3, 0xc0, v3
	v_and_b32_e32 v2, -16, v2
	v_sub_u32_e32 v1, v1, v3
	v_mov_b32_e32 v3, 1
	v_add_u32_e32 v2, v9, v2
	v_ashrrev_i16_sdwa v1, v3, sext(v1) dst_sel:DWORD dst_unused:UNUSED_PAD src0_sel:DWORD src1_sel:BYTE_0
	v_lshlrev_b32_e32 v4, 5, v8
	v_bfe_i32 v10, v1, 0, 16
	v_lshlrev_b32_e32 v1, 1, v2
	v_lshrrev_b32_e32 v5, 2, v2
	v_and_b32_e32 v6, 3, v9
	s_mov_b32 s1, 0xfffe0
	v_and_b32_e32 v4, 32, v4
	v_and_b32_e32 v1, 24, v1
	v_and_b32_e32 v5, 4, v5
	v_and_or_b32 v6, v2, s1, v6
	v_or3_b32 v1, v6, v5, v1
	v_add_lshl_u32 v4, v4, v10, 1
	v_add_u32_e32 v0, 0x2000, v0
	v_lshl_add_u32 v130, v1, 12, v4
	v_ashrrev_i32_e32 v1, 31, v0
	v_lshrrev_b32_e32 v1, 22, v1
	v_add_u32_e32 v1, v0, v1
	v_ashrrev_i32_e32 v11, 10, v1
	v_mul_i32_i24_e32 v1, 0x400, v11
	v_sub_u32_e32 v0, v0, v1
	v_lshrrev_b32_e32 v1, 4, v0
	v_bitop3_b32 v0, v1, v0, 32 bitop3:0x6c
	v_lshl_add_u32 v128, v2, 12, v4
	v_ashrrev_i32_e32 v2, 31, v0
	v_lshrrev_b32_e32 v2, 26, v2
	v_add_u32_e32 v2, v0, v2
	v_ashrrev_i32_e32 v12, 6, v2
	v_and_b32_e32 v2, 0xffc0, v2
	s_cmp_eq_u32 s0, 1
	v_sub_u32_e32 v0, v0, v2
	s_cselect_b64 s[4:5], -1, 0
	v_lshrrev_b16_e32 v2, 7, v0
	v_writelane_b32 v248, s4, 45
	v_lshlrev_b32_e32 v1, 3, v11
	v_and_b32_e32 v2, 1, v2
	v_writelane_b32 v248, s5, 46
	s_ashr_i32 s45, s44, 31
	s_ashr_i32 s19, s18, 31
	v_and_b32_e32 v1, -16, v1
	v_add_u16_e32 v0, v0, v2
	s_lshl_b64 s[4:5], s[44:45], 20
	s_lshl_b64 s[6:7], s[18:19], 20
	v_readlane_b32 s8, v248, 25
	v_add_u32_e32 v1, v12, v1
	v_ashrrev_i16_sdwa v0, v3, sext(v0) dst_sel:DWORD dst_unused:UNUSED_PAD src0_sel:DWORD src1_sel:BYTE_0
	v_readlane_b32 s9, v248, 26
	s_add_u32 s48, s8, s6
	v_lshlrev_b32_e32 v4, 5, v11
	v_bfe_i32 v13, v0, 0, 16
	v_lshlrev_b32_e32 v0, 1, v1
	v_lshrrev_b32_e32 v2, 2, v1
	v_and_b32_e32 v3, 3, v12
	s_addc_u32 s49, s9, s7
	s_add_i32 s53, s52, 0
	v_and_b32_e32 v4, 32, v4
	v_and_b32_e32 v0, 24, v0
	v_and_b32_e32 v2, 4, v2
	v_and_or_b32 v3, v1, s1, v3
	s_add_i32 m0, s53, 0x10000
	s_add_i32 s1, s53, 0x12000
	v_or3_b32 v0, v3, v2, v0
	v_add_lshl_u32 v2, v4, v13, 1
	s_add_u32 s6, s48, 0x80000
	v_lshl_add_u32 v134, v0, 12, v2
	s_addc_u32 s7, s49, 0
	s_add_i32 s8, s53, 0x14000
	s_add_i32 s9, s53, 0x16000
	v_readlane_b32 s10, v248, 27
	global_load_lds_dwordx4 v130, s[48:49]
	s_mov_b32 m0, s1
	v_readlane_b32 s11, v248, 28
	s_add_u32 s46, s10, s4
	global_load_lds_dwordx4 v134, s[48:49]
	s_mov_b32 m0, s8
	s_addc_u32 s47, s11, s5
	s_add_i32 s54, s53, 0x2000
	global_load_lds_dwordx4 v130, s[6:7]
	s_mov_b32 m0, s9
	s_add_u32 s4, s46, 0x80000
	global_load_lds_dwordx4 v134, s[6:7]
	s_mov_b32 m0, s53
	v_lshl_add_u32 v132, v1, 12, v2
	s_addc_u32 s5, s47, 0
	s_add_i32 s55, s53, 0x4000
	global_load_lds_dwordx4 v128, s[46:47]
	s_mov_b32 m0, s54
	s_add_i32 s56, s53, 0x6000
	global_load_lds_dwordx4 v132, s[46:47]
	s_mov_b32 m0, s55
	v_mov_b32_e32 v129, v131
	global_load_lds_dwordx4 v128, s[4:5]
	s_mov_b32 m0, s56
	v_mov_b32_e32 v133, v131
	global_load_lds_dwordx4 v132, s[4:5]
	s_mov_b32 s45, 0
	s_cmp_lg_u32 s0, 1
	v_lshl_add_u64 v[6:7], s[48:49], 0, v[130:131]
	v_lshl_add_u64 v[4:5], s[48:49], 0, v[134:135]
	v_lshl_add_u64 v[2:3], s[46:47], 0, v[128:129]
	v_lshl_add_u64 v[0:1], s[46:47], 0, v[132:133]
	s_cbranch_scc1 .LBB0_123
	s_barrier
